# v38 plus P0 weight transposes of w_in and w_up issue all loads of an item before the first wait (was one or two loads in flight)
# speedup vs baseline: 1.0136x; 1.0101x over previous
.LBB0_21:
	s_and_b64 vcc, exec, s[4:5]
	s_cbranch_vccz .LBB0_41
	s_lshl_b32 s4, s60, 2
	s_and_b32 s4, s4, 0x7f80
	v_lshl_or_b32 v5, v25, 2, s4
	s_bfe_u32 s4, s33, 0x80008
	s_lshl_b32 s5, s4, 6
	v_or_b32_e32 v6, s5, v62
	v_lshl_or_b32 v6, v6, 15, v5
	v_lshl_add_u64 v[34:35], s[48:49], 0, v[6:7]
	v_or_b32_e32 v6, s5, v63
	v_lshl_or_b32 v6, v6, 15, v5
	v_lshl_add_u64 v[38:39], s[48:49], 0, v[6:7]
	v_or_b32_e32 v6, s5, v64
	v_lshl_or_b32 v6, v6, 15, v5
	v_lshl_add_u64 v[40:41], s[48:49], 0, v[6:7]
	v_or_b32_e32 v6, s5, v65
	v_lshl_or_b32 v6, v6, 15, v5
	v_lshl_add_u64 v[42:43], s[48:49], 0, v[6:7]
	v_or_b32_e32 v6, s5, v66
	v_lshl_or_b32 v6, v6, 15, v5
	v_lshl_add_u64 v[44:45], s[48:49], 0, v[6:7]
	v_or_b32_e32 v6, s5, v67
	v_lshl_or_b32 v6, v6, 15, v5
	v_lshl_add_u64 v[46:47], s[48:49], 0, v[6:7]
	v_or_b32_e32 v6, s5, v68
	v_lshl_or_b32 v6, v6, 15, v5
	v_or_b32_e32 v50, s5, v2
	v_lshl_add_u64 v[48:49], s[48:49], 0, v[6:7]
	v_lshlrev_b32_e32 v6, 2, v50
	v_lshl_or_b32 v50, v50, 15, v5
	v_mov_b32_e32 v51, v7
	v_lshl_or_b32 v36, s4, 8, v32
	v_mov_b32_e32 v37, v3
	v_lshl_add_u64 v[50:51], s[48:49], 0, v[50:51]
	s_mov_b64 s[18:19], 0
	s_mov_b64 s[58:59], s[46:47]
	v_mov_b32_e32 v5, v61
	s_and_b64 vcc, exec, s[22:23]
	s_cbranch_vccz .LBB0_24
	global_load_dword v100, v[50:51], off
	global_load_dword v101, v[48:49], off
	global_load_dword v102, v[46:47], off
	global_load_dword v103, v[44:45], off
	global_load_dword v104, v[42:43], off
	global_load_dword v105, v[40:41], off
	global_load_dword v106, v[38:39], off
	global_load_dword v107, v[34:35], off
	v_lshl_add_u64 v[166:167], s[58:59], 0, v[6:7]
	global_load_dword v132, v[166:167], off
	v_lshl_add_u64 v[166:167], s[58:59], 0, v[36:37]
	global_load_dword v133, v[166:167], off offset:8
	v_lshl_add_u64 v[166:167], s[58:59], 0, v[36:37]
	global_load_dword v134, v[166:167], off offset:16
	v_lshl_add_u64 v[166:167], s[58:59], 0, v[36:37]
	global_load_dword v135, v[166:167], off offset:24
	v_lshl_add_u64 v[166:167], s[58:59], 0, v[36:37]
	global_load_dword v136, v[166:167], off offset:32
	v_lshl_add_u64 v[166:167], s[58:59], 0, v[36:37]
	global_load_dword v137, v[166:167], off offset:40
	v_lshl_add_u64 v[166:167], s[58:59], 0, v[36:37]
	global_load_dword v138, v[166:167], off offset:48
	v_lshl_add_u64 v[166:167], s[58:59], 0, v[36:37]
	global_load_dword v139, v[166:167], off offset:56
	s_mov_b32 s18, 0x80000
	s_mov_b32 s19, 0
	v_lshl_add_u64 v[164:165], v[50:51], 0, s[18:19]
	global_load_dword v108, v[164:165], off
	v_lshl_add_u64 v[164:165], v[48:49], 0, s[18:19]
	global_load_dword v109, v[164:165], off
	v_lshl_add_u64 v[164:165], v[46:47], 0, s[18:19]
	global_load_dword v110, v[164:165], off
	v_lshl_add_u64 v[164:165], v[44:45], 0, s[18:19]
	global_load_dword v111, v[164:165], off
	v_lshl_add_u64 v[164:165], v[42:43], 0, s[18:19]
	global_load_dword v112, v[164:165], off
	v_lshl_add_u64 v[164:165], v[40:41], 0, s[18:19]
	global_load_dword v113, v[164:165], off
	v_lshl_add_u64 v[164:165], v[38:39], 0, s[18:19]
	global_load_dword v114, v[164:165], off
	v_lshl_add_u64 v[164:165], v[34:35], 0, s[18:19]
	global_load_dword v115, v[164:165], off
	v_lshl_add_u64 v[166:167], s[58:59], 0, v[6:7]
	global_load_dword v140, v[166:167], off offset:64
	v_lshl_add_u64 v[166:167], s[58:59], 0, v[36:37]
	global_load_dword v141, v[166:167], off offset:72
	v_lshl_add_u64 v[166:167], s[58:59], 0, v[36:37]
	global_load_dword v142, v[166:167], off offset:80
	v_lshl_add_u64 v[166:167], s[58:59], 0, v[36:37]
	global_load_dword v143, v[166:167], off offset:88
	v_lshl_add_u64 v[166:167], s[58:59], 0, v[36:37]
	global_load_dword v144, v[166:167], off offset:96
	v_lshl_add_u64 v[166:167], s[58:59], 0, v[36:37]
	global_load_dword v145, v[166:167], off offset:104
	v_lshl_add_u64 v[166:167], s[58:59], 0, v[36:37]
	global_load_dword v146, v[166:167], off offset:112
	v_lshl_add_u64 v[166:167], s[58:59], 0, v[36:37]
	global_load_dword v147, v[166:167], off offset:120
	s_waitcnt vmcnt(16)
	v_mul_f32_e32 v100, v100, v132
	v_mul_f32_e32 v101, v101, v133
	v_mul_f32_e32 v102, v102, v134
	v_mul_f32_e32 v103, v103, v135
	v_mul_f32_e32 v104, v104, v136
	v_mul_f32_e32 v105, v105, v137
	v_mul_f32_e32 v106, v106, v138
	v_mul_f32_e32 v107, v107, v139
	ds_write_b32 v5, v100
	ds_write_b32 v5, v101 offset:264
	ds_write_b32 v5, v102 offset:528
	ds_write_b32 v5, v103 offset:792
	ds_write_b32 v5, v104 offset:1056
	ds_write_b32 v5, v105 offset:1320
	ds_write_b32 v5, v106 offset:1584
	ds_write_b32 v5, v107 offset:1848
	s_waitcnt vmcnt(0)
	v_mul_f32_e32 v108, v108, v140
	v_mul_f32_e32 v109, v109, v141
	v_mul_f32_e32 v110, v110, v142
	v_mul_f32_e32 v111, v111, v143
	v_mul_f32_e32 v112, v112, v144
	v_mul_f32_e32 v113, v113, v145
	v_mul_f32_e32 v114, v114, v146
	v_mul_f32_e32 v115, v115, v147
	ds_write_b32 v5, v108 offset:2112
	ds_write_b32 v5, v109 offset:2376
	ds_write_b32 v5, v110 offset:2640
	ds_write_b32 v5, v111 offset:2904
	ds_write_b32 v5, v112 offset:3168
	ds_write_b32 v5, v113 offset:3432
	ds_write_b32 v5, v114 offset:3696
	ds_write_b32 v5, v115 offset:3960
	s_mov_b32 s18, 0x100000
	s_mov_b32 s19, 0
	v_lshl_add_u64 v[164:165], v[50:51], 0, s[18:19]
	global_load_dword v100, v[164:165], off
	v_lshl_add_u64 v[164:165], v[48:49], 0, s[18:19]
	global_load_dword v101, v[164:165], off
	v_lshl_add_u64 v[164:165], v[46:47], 0, s[18:19]
	global_load_dword v102, v[164:165], off
	v_lshl_add_u64 v[164:165], v[44:45], 0, s[18:19]
	global_load_dword v103, v[164:165], off
	v_lshl_add_u64 v[164:165], v[42:43], 0, s[18:19]
	global_load_dword v104, v[164:165], off
	v_lshl_add_u64 v[164:165], v[40:41], 0, s[18:19]
	global_load_dword v105, v[164:165], off
	v_lshl_add_u64 v[164:165], v[38:39], 0, s[18:19]
	global_load_dword v106, v[164:165], off
	v_lshl_add_u64 v[164:165], v[34:35], 0, s[18:19]
	global_load_dword v107, v[164:165], off
	v_lshl_add_u64 v[166:167], s[58:59], 0, v[6:7]
	global_load_dword v132, v[166:167], off offset:128
	v_lshl_add_u64 v[166:167], s[58:59], 0, v[36:37]
	global_load_dword v133, v[166:167], off offset:136
	v_lshl_add_u64 v[166:167], s[58:59], 0, v[36:37]
	global_load_dword v134, v[166:167], off offset:144
	v_lshl_add_u64 v[166:167], s[58:59], 0, v[36:37]
	global_load_dword v135, v[166:167], off offset:152
	v_lshl_add_u64 v[166:167], s[58:59], 0, v[36:37]
	global_load_dword v136, v[166:167], off offset:160
	v_lshl_add_u64 v[166:167], s[58:59], 0, v[36:37]
	global_load_dword v137, v[166:167], off offset:168
	v_lshl_add_u64 v[166:167], s[58:59], 0, v[36:37]
	global_load_dword v138, v[166:167], off offset:176
	v_lshl_add_u64 v[166:167], s[58:59], 0, v[36:37]
	global_load_dword v139, v[166:167], off offset:184
	s_mov_b32 s18, 0x180000
	s_mov_b32 s19, 0
	v_lshl_add_u64 v[164:165], v[50:51], 0, s[18:19]
	global_load_dword v108, v[164:165], off
	v_lshl_add_u64 v[164:165], v[48:49], 0, s[18:19]
	global_load_dword v109, v[164:165], off
	v_lshl_add_u64 v[164:165], v[46:47], 0, s[18:19]
	global_load_dword v110, v[164:165], off
	v_lshl_add_u64 v[164:165], v[44:45], 0, s[18:19]
	global_load_dword v111, v[164:165], off
	v_lshl_add_u64 v[164:165], v[42:43], 0, s[18:19]
	global_load_dword v112, v[164:165], off
	v_lshl_add_u64 v[164:165], v[40:41], 0, s[18:19]
	global_load_dword v113, v[164:165], off
	v_lshl_add_u64 v[164:165], v[38:39], 0, s[18:19]
	global_load_dword v114, v[164:165], off
	v_lshl_add_u64 v[164:165], v[34:35], 0, s[18:19]
	global_load_dword v115, v[164:165], off
	v_lshl_add_u64 v[166:167], s[58:59], 0, v[6:7]
	global_load_dword v140, v[166:167], off offset:192
	v_lshl_add_u64 v[166:167], s[58:59], 0, v[36:37]
	global_load_dword v141, v[166:167], off offset:200
	v_lshl_add_u64 v[166:167], s[58:59], 0, v[36:37]
	global_load_dword v142, v[166:167], off offset:208
	v_lshl_add_u64 v[166:167], s[58:59], 0, v[36:37]
	global_load_dword v143, v[166:167], off offset:216
	v_lshl_add_u64 v[166:167], s[58:59], 0, v[36:37]
	global_load_dword v144, v[166:167], off offset:224
	v_lshl_add_u64 v[166:167], s[58:59], 0, v[36:37]
	global_load_dword v145, v[166:167], off offset:232
	v_lshl_add_u64 v[166:167], s[58:59], 0, v[36:37]
	global_load_dword v146, v[166:167], off offset:240
	v_lshl_add_u64 v[166:167], s[58:59], 0, v[36:37]
	global_load_dword v147, v[166:167], off offset:248
	s_waitcnt vmcnt(16)
	v_mul_f32_e32 v100, v100, v132
	v_mul_f32_e32 v101, v101, v133
	v_mul_f32_e32 v102, v102, v134
	v_mul_f32_e32 v103, v103, v135
	v_mul_f32_e32 v104, v104, v136
	v_mul_f32_e32 v105, v105, v137
	v_mul_f32_e32 v106, v106, v138
	v_mul_f32_e32 v107, v107, v139
	ds_write_b32 v5, v100 offset:4224
	ds_write_b32 v5, v101 offset:4488
	ds_write_b32 v5, v102 offset:4752
	ds_write_b32 v5, v103 offset:5016
	ds_write_b32 v5, v104 offset:5280
	ds_write_b32 v5, v105 offset:5544
	ds_write_b32 v5, v106 offset:5808
	ds_write_b32 v5, v107 offset:6072
	s_waitcnt vmcnt(0)
	v_mul_f32_e32 v108, v108, v140
	v_mul_f32_e32 v109, v109, v141
	v_mul_f32_e32 v110, v110, v142
	v_mul_f32_e32 v111, v111, v143
	v_mul_f32_e32 v112, v112, v144
	v_mul_f32_e32 v113, v113, v145
	v_mul_f32_e32 v114, v114, v146
	v_mul_f32_e32 v115, v115, v147
	ds_write_b32 v5, v108 offset:6336
	ds_write_b32 v5, v109 offset:6600
	ds_write_b32 v5, v110 offset:6864
	ds_write_b32 v5, v111 offset:7128
	ds_write_b32 v5, v112 offset:7392
	ds_write_b32 v5, v113 offset:7656
	ds_write_b32 v5, v114 offset:7920
	ds_write_b32 v5, v115 offset:8184
	v_add_u32_e32 v5, 0x2100, v5
	s_mov_b32 s18, 0x200000
	s_mov_b32 s19, 0
	s_add_u32 s58, s58, 0x100
	s_addc_u32 s59, s59, 0
	s_branch .LBB0_40

.LBB0_118:
	s_lshl_b32 s4, s18, 6
	v_or_b32_e32 v5, s4, v62
	v_lshlrev_b64 v[48:49], 2, v[6:7]
	v_mad_i64_i32 v[34:35], s[18:19], v5, s67, v[48:49]
	v_or_b32_e32 v5, s4, v63
	v_mad_i64_i32 v[36:37], s[18:19], v5, s67, v[48:49]
	v_or_b32_e32 v5, s4, v64
	v_mad_i64_i32 v[38:39], s[18:19], v5, s67, v[48:49]
	v_or_b32_e32 v5, s4, v65
	v_mad_i64_i32 v[40:41], s[18:19], v5, s67, v[48:49]
	v_or_b32_e32 v5, s4, v66
	v_mad_i64_i32 v[42:43], s[18:19], v5, s67, v[48:49]
	v_or_b32_e32 v5, s4, v67
	v_mad_i64_i32 v[44:45], s[18:19], v5, s67, v[48:49]
	v_or_b32_e32 v5, s4, v68
	v_mad_i64_i32 v[46:47], s[18:19], v5, s67, v[48:49]
	v_or_b32_e32 v5, s4, v2
	v_mad_i64_i32 v[48:49], s[18:19], v5, s67, v[48:49]
	v_cmp_lt_i32_e32 vcc, -1, v6
	v_lshl_add_u64 v[34:35], s[24:25], 0, v[34:35]
	v_lshl_add_u64 v[36:37], s[24:25], 0, v[36:37]
	v_lshl_add_u64 v[38:39], s[24:25], 0, v[38:39]
	v_lshl_add_u64 v[40:41], s[24:25], 0, v[40:41]
	v_lshl_add_u64 v[42:43], s[24:25], 0, v[42:43]
	v_lshl_add_u64 v[44:45], s[24:25], 0, v[44:45]
	v_lshl_add_u64 v[46:47], s[24:25], 0, v[46:47]
	v_lshl_add_u64 v[48:49], s[24:25], 0, v[48:49]
	s_mov_b64 s[18:19], 0
	v_mov_b32_e32 v5, v61
	v_mov_b32_e32 v100, 0
	v_mov_b32_e32 v101, 0
	v_mov_b32_e32 v102, 0
	v_mov_b32_e32 v103, 0
	v_mov_b32_e32 v104, 0
	v_mov_b32_e32 v105, 0
	v_mov_b32_e32 v106, 0
	v_mov_b32_e32 v107, 0
	v_mov_b32_e32 v108, 0
	v_mov_b32_e32 v109, 0
	v_mov_b32_e32 v110, 0
	v_mov_b32_e32 v111, 0
	v_mov_b32_e32 v112, 0
	v_mov_b32_e32 v113, 0
	v_mov_b32_e32 v114, 0
	v_mov_b32_e32 v115, 0
	v_mov_b32_e32 v116, 0
	v_mov_b32_e32 v117, 0
	v_mov_b32_e32 v118, 0
	v_mov_b32_e32 v119, 0
	v_mov_b32_e32 v120, 0
	v_mov_b32_e32 v121, 0
	v_mov_b32_e32 v122, 0
	v_mov_b32_e32 v123, 0
	v_mov_b32_e32 v124, 0
	v_mov_b32_e32 v125, 0
	v_mov_b32_e32 v126, 0
	v_mov_b32_e32 v127, 0
	v_mov_b32_e32 v128, 0
	v_mov_b32_e32 v129, 0
	v_mov_b32_e32 v130, 0
	v_mov_b32_e32 v131, 0
	s_and_saveexec_b64 s[56:57], vcc
	global_load_dword v100, v[48:49], off
	global_load_dword v101, v[46:47], off
	global_load_dword v102, v[44:45], off
	global_load_dword v103, v[42:43], off
	global_load_dword v104, v[40:41], off
	global_load_dword v105, v[38:39], off
	global_load_dword v106, v[36:37], off
	global_load_dword v107, v[34:35], off
	s_mov_b32 s18, 0xc9000
	s_mov_b32 s19, 0
	v_lshl_add_u64 v[50:51], v[48:49], 0, s[18:19]
	global_load_dword v108, v[50:51], off
	v_lshl_add_u64 v[50:51], v[46:47], 0, s[18:19]
	global_load_dword v109, v[50:51], off
	v_lshl_add_u64 v[50:51], v[44:45], 0, s[18:19]
	global_load_dword v110, v[50:51], off
	v_lshl_add_u64 v[50:51], v[42:43], 0, s[18:19]
	global_load_dword v111, v[50:51], off
	v_lshl_add_u64 v[50:51], v[40:41], 0, s[18:19]
	global_load_dword v112, v[50:51], off
	v_lshl_add_u64 v[50:51], v[38:39], 0, s[18:19]
	global_load_dword v113, v[50:51], off
	v_lshl_add_u64 v[50:51], v[36:37], 0, s[18:19]
	global_load_dword v114, v[50:51], off
	v_lshl_add_u64 v[50:51], v[34:35], 0, s[18:19]
	global_load_dword v115, v[50:51], off
	s_mov_b32 s18, 0x192000
	s_mov_b32 s19, 0
	v_lshl_add_u64 v[50:51], v[48:49], 0, s[18:19]
	global_load_dword v116, v[50:51], off
	v_lshl_add_u64 v[50:51], v[46:47], 0, s[18:19]
	global_load_dword v117, v[50:51], off
	v_lshl_add_u64 v[50:51], v[44:45], 0, s[18:19]
	global_load_dword v118, v[50:51], off
	v_lshl_add_u64 v[50:51], v[42:43], 0, s[18:19]
	global_load_dword v119, v[50:51], off
	v_lshl_add_u64 v[50:51], v[40:41], 0, s[18:19]
	global_load_dword v120, v[50:51], off
	v_lshl_add_u64 v[50:51], v[38:39], 0, s[18:19]
	global_load_dword v121, v[50:51], off
	v_lshl_add_u64 v[50:51], v[36:37], 0, s[18:19]
	global_load_dword v122, v[50:51], off
	v_lshl_add_u64 v[50:51], v[34:35], 0, s[18:19]
	global_load_dword v123, v[50:51], off
	s_mov_b32 s18, 0x25b000
	s_mov_b32 s19, 0
	v_lshl_add_u64 v[50:51], v[48:49], 0, s[18:19]
	global_load_dword v124, v[50:51], off
	v_lshl_add_u64 v[50:51], v[46:47], 0, s[18:19]
	global_load_dword v125, v[50:51], off
	v_lshl_add_u64 v[50:51], v[44:45], 0, s[18:19]
	global_load_dword v126, v[50:51], off
	v_lshl_add_u64 v[50:51], v[42:43], 0, s[18:19]
	global_load_dword v127, v[50:51], off
	v_lshl_add_u64 v[50:51], v[40:41], 0, s[18:19]
	global_load_dword v128, v[50:51], off
	v_lshl_add_u64 v[50:51], v[38:39], 0, s[18:19]
	global_load_dword v129, v[50:51], off
	v_lshl_add_u64 v[50:51], v[36:37], 0, s[18:19]
	global_load_dword v130, v[50:51], off
	v_lshl_add_u64 v[50:51], v[34:35], 0, s[18:19]
	global_load_dword v131, v[50:51], off
	s_or_b64 exec, exec, s[56:57]
	s_waitcnt vmcnt(24)
	ds_write_b32 v5, v100
	ds_write_b32 v5, v101 offset:264
	ds_write_b32 v5, v102 offset:528
	ds_write_b32 v5, v103 offset:792
	ds_write_b32 v5, v104 offset:1056
	ds_write_b32 v5, v105 offset:1320
	ds_write_b32 v5, v106 offset:1584
	ds_write_b32 v5, v107 offset:1848
	s_waitcnt vmcnt(16)
	ds_write_b32 v5, v108 offset:2112
	ds_write_b32 v5, v109 offset:2376
	ds_write_b32 v5, v110 offset:2640
	ds_write_b32 v5, v111 offset:2904
	ds_write_b32 v5, v112 offset:3168
	ds_write_b32 v5, v113 offset:3432
	ds_write_b32 v5, v114 offset:3696
	ds_write_b32 v5, v115 offset:3960
	s_waitcnt vmcnt(8)
	ds_write_b32 v5, v116 offset:4224
	ds_write_b32 v5, v117 offset:4488
	ds_write_b32 v5, v118 offset:4752
	ds_write_b32 v5, v119 offset:5016
	ds_write_b32 v5, v120 offset:5280
	ds_write_b32 v5, v121 offset:5544
	ds_write_b32 v5, v122 offset:5808
	ds_write_b32 v5, v123 offset:6072
	s_waitcnt vmcnt(0)
	ds_write_b32 v5, v124 offset:6336
	ds_write_b32 v5, v125 offset:6600
	ds_write_b32 v5, v126 offset:6864
	ds_write_b32 v5, v127 offset:7128
	ds_write_b32 v5, v128 offset:7392
	ds_write_b32 v5, v129 offset:7656
	ds_write_b32 v5, v130 offset:7920
	ds_write_b32 v5, v131 offset:8184
	v_add_u32_e32 v5, 0x2100, v5
	s_mov_b32 s18, 0x324000
	s_mov_b32 s19, 0
	s_branch .LBB0_7
